# ssm1/ssm2 items: bbre/bbim/lambda parameter loads issued before the item's barriers (with the u-row loads) into free VGPRs, copied at the original place
# baseline (speedup 1.0000x reference)
; DI int tidx() { int t = threadIdx.x & 255; asm volatile("" : "+v"(t)); return t; }
; DI void ssm_stage_u(PREF p, int b, int c, int gq, float* uS) {
;   const int tid = tidx();
;   int row = tid >> 2, cc = (tid & 3) * 16;
;   const u16* src = p.hb + (size_t)(b * S_ + c * 64 + row) * HW + OFF_U + gq * 64 + cc;
;   float f[16];
;   unpack8(*(const u32x4*)src, f); unpack8(*(const u32x4*)(src + 8), f + 8);
; #pragma unroll
;   for (int j = 0; j < 4; ++j) *(float4*)(uS + row * 64 + cc + 4 * j) = make_float4(f[4 * j], f[4 * j + 1], f[4 * j + 2], f[4 * j + 3]);
; }
; DI void ssm2_item(PREF p, int l, int item, unsigned char* ldsb) {
;     ...
;   __syncthreads();
;   ssm_stage_u(p, b, c, gq, uS);
;   __syncthreads();
;   const size_t pi = (size_t)(l * 16 + g) * 64 + lane;
;   float bre[16], bim[16];
; #pragma unroll
;   for (int j = 0; j < 16; ++j) { bre[j] = p.bbre[pi * 16 + j]; bim[j] = p.bbim[pi * 16 + j]; }
;   const float lr = p.lam[pi * 2], li = p.lam[pi * 2 + 1];
.LBB0_268:
	s_lshr_b32 s0, s48, 9
	s_lshl_b32 s0, s0, 4
	s_lshr_b32 s63, s48, 2
	s_add_i32 s63, s63, s0
	s_and_b32 s63, s63, 63
	s_ashr_i32 s8, s48, 8
	v_mov_b32_e32 v79, v169
	v_mov_b32_e32 v0, v169
	s_lshl_b32 s0, s8, 12
	s_lshl_b32 s1, s63, 6
	s_barrier
	s_or_b32 s62, s1, s0
	s_load_dwordx2 s[0:1], s[10:11], 0x140
	v_ashrrev_i32_e32 v10, 2, v0
	v_lshlrev_b32_e32 v0, 4, v0
	s_and_b32 s9, s48, 3
	v_and_b32_e32 v11, 48, v0
	v_add_u32_e32 v0, s62, v10
	s_waitcnt lgkmcnt(0)
	v_mov_b64_e32 v[2:3], s[0:1]
	v_mad_i64_i32 v[2:3], s[0:1], v0, s60, v[2:3]
	s_lshl_b32 s52, s9, 7
	v_lshl_add_u64 v[2:3], v[2:3], 0, s[52:53]
	v_lshlrev_b32_e32 v0, 1, v11
	v_lshl_add_u64 v[6:7], v[2:3], 0, v[0:1]
	global_load_dwordx4 v[2:5], v[6:7], off offset:2880
	s_nop 0
	global_load_dwordx4 v[6:9], v[6:7], off offset:2896
	v_ashrrev_i32_e32 v80, 6, v79
	v_lshl_add_u32 v81, s9, 2, v80
	v_add_u32_e32 v22, s49, v81
	s_load_dwordx2 s[0:1], s[10:11], 0x118
	v_lshlrev_b32_e32 v0, 8, v10
	v_lshlrev_b32_e32 v10, 2, v11
	v_ashrrev_i32_e32 v23, 31, v22
	v_and_b32_e32 v78, 63, v79
	v_add3_u32 v0, s33, v0, v10
	v_lshlrev_b64 v[10:11], 6, v[22:23]
	v_or_b32_e32 v10, v10, v78
	v_lshlrev_b64 v[12:13], 6, v[10:11]
	v_lshl_add_u64 v[24:25], v[10:11], 3, s[40:41]
	v_lshl_add_u64 v[18:19], s[42:43], 0, v[12:13]
	s_waitcnt lgkmcnt(0)
	v_lshl_add_u64 v[20:21], s[0:1], 0, v[12:13]
	s_cmp_eq_u32 s63, 0
	global_load_dwordx4 v[26:29], v[18:19], off offset:48
	global_load_dwordx4 v[82:85], v[18:19], off offset:32
	global_load_dwordx4 v[86:89], v[18:19], off offset:16
	global_load_dwordx4 v[90:93], v[18:19], off
	global_load_dwordx4 v[94:97], v[20:21], off offset:48
	global_load_dwordx4 v[98:101], v[20:21], off offset:32
	global_load_dwordx4 v[102:105], v[20:21], off offset:16
	global_load_dwordx4 v[106:109], v[20:21], off
	global_load_dwordx2 v[110:111], v[24:25], off
	s_waitcnt vmcnt(10)
	v_lshlrev_b32_e32 v10, 16, v2
	v_and_b32_e32 v11, 0xffff0000, v2
	v_lshlrev_b32_e32 v12, 16, v3
	v_and_b32_e32 v13, 0xffff0000, v3
	v_lshlrev_b32_e32 v2, 16, v4
	v_and_b32_e32 v3, 0xffff0000, v4
	v_lshlrev_b32_e32 v4, 16, v5
	v_and_b32_e32 v5, 0xffff0000, v5
	s_waitcnt vmcnt(9)
	v_lshlrev_b32_e32 v14, 16, v6
	v_and_b32_e32 v15, 0xffff0000, v6
	v_lshlrev_b32_e32 v16, 16, v7
	v_and_b32_e32 v17, 0xffff0000, v7
	v_lshlrev_b32_e32 v6, 16, v8
	v_and_b32_e32 v7, 0xffff0000, v8
	v_lshlrev_b32_e32 v8, 16, v9
	v_and_b32_e32 v9, 0xffff0000, v9
	ds_write_b128 v0, v[10:13]
	ds_write_b128 v0, v[2:5] offset:16
	ds_write_b128 v0, v[14:17] offset:32
	ds_write_b128 v0, v[6:9] offset:48
	s_waitcnt lgkmcnt(0)
	s_barrier
	s_waitcnt vmcnt(0)
	v_mov_b32_e32 v42, v26
	v_mov_b32_e32 v43, v27
	v_mov_b32_e32 v44, v28
	v_mov_b32_e32 v45, v29
	v_mov_b32_e32 v46, v82
	v_mov_b32_e32 v47, v83
	v_mov_b32_e32 v48, v84
	v_mov_b32_e32 v49, v85
	v_mov_b32_e32 v2, v86
	v_mov_b32_e32 v3, v87
	v_mov_b32_e32 v4, v88
	v_mov_b32_e32 v5, v89
	v_mov_b32_e32 v38, v90
	v_mov_b32_e32 v39, v91
	v_mov_b32_e32 v40, v92
	v_mov_b32_e32 v41, v93
	v_mov_b32_e32 v6, v94
	v_mov_b32_e32 v7, v95
	v_mov_b32_e32 v8, v96
	v_mov_b32_e32 v9, v97
	v_mov_b32_e32 v10, v98
	v_mov_b32_e32 v11, v99
	v_mov_b32_e32 v12, v100
	v_mov_b32_e32 v13, v101
	v_mov_b32_e32 v14, v102
	v_mov_b32_e32 v15, v103
	v_mov_b32_e32 v16, v104
	v_mov_b32_e32 v17, v105
	s_nop 0
	v_mov_b32_e32 v18, v106
	v_mov_b32_e32 v19, v107
	v_mov_b32_e32 v20, v108
	v_mov_b32_e32 v21, v109
	s_nop 0
	v_mov_b32_e32 v50, v110
	v_mov_b32_e32 v51, v111
	s_cbranch_scc1 .LBB0_302
	s_waitcnt vmcnt(0)
	v_pk_mul_f32 v[24:25], v[50:51], v[50:51]
	s_and_b32 s0, s57, 3
	v_sub_f32_e32 v0, v24, v25
	v_add_f32_e32 v24, v50, v50
	v_mul_f32_e32 v24, v51, v24
	v_mul_f32_e32 v25, v0, v0
	v_add_f32_e32 v0, v0, v0
	v_mul_f32_e32 v0, v24, v0
	v_fma_f32 v25, -v24, v24, v25
	v_mul_f32_e32 v24, v0, v0
	v_fma_f32 v24, v25, v25, -v24
	v_add_f32_e32 v25, v25, v25
	v_mul_f32_e32 v0, v0, v25
	v_mul_f32_e32 v25, v0, v0
	v_fma_f32 v25, v24, v24, -v25
	v_add_f32_e32 v24, v24, v24
	s_lshl_b32 s0, s0, 2
	v_mul_f32_e32 v0, v0, v24
	s_lshl_b32 s1, s8, 4
	v_mul_f32_e32 v24, v0, v0
	s_or_b32 s0, s0, s1
	v_fma_f32 v26, v25, v25, -v24
	v_add_f32_e32 v24, v25, v25
	v_add_u32_e32 v28, s0, v80
	v_mul_f32_e32 v0, v0, v24
	v_ashrrev_i32_e32 v29, 31, v28
	v_mul_f32_e32 v24, v0, v0
	v_add_f32_e32 v25, v26, v26
	v_lshlrev_b64 v[28:29], 15, v[28:29]
	v_fma_f32 v24, v26, v26, -v24
	v_mul_f32_e32 v26, v0, v25
	v_lshl_or_b32 v28, v78, 3, v28
	v_mov_b32_e32 v25, v24
	v_mov_b32_e32 v27, v26
	v_lshl_add_u64 v[28:29], s[68:69], 0, v[28:29]
	s_mov_b32 s52, 0
	v_mov_b32_e32 v52, 0
	v_mov_b32_e32 v53, 0
	s_branch .LBB0_271

; DI int tidx() { int t = threadIdx.x & 255; asm volatile("" : "+v"(t)); return t; }
; DI void ssm_stage_u(PREF p, int b, int c, int gq, float* uS) {
;   const int tid = tidx();
;   int row = tid >> 2, cc = (tid & 3) * 16;
;   const u16* src = p.hb + (size_t)(b * S_ + c * 64 + row) * HW + OFF_U + gq * 64 + cc;
;   float f[16];
;   unpack8(*(const u32x4*)src, f); unpack8(*(const u32x4*)(src + 8), f + 8);
; #pragma unroll
;   for (int j = 0; j < 4; ++j) *(float4*)(uS + row * 64 + cc + 4 * j) = make_float4(f[4 * j], f[4 * j + 1], f[4 * j + 2], f[4 * j + 3]);
; }
; DI void ssm1_item(PREF p, int l, int item, unsigned char* ldsb) {
;     ...
;   __syncthreads();
;   ssm_stage_u(p, b, c, gq, uS);
;   __syncthreads();
;   const size_t pi = (size_t)(l * 16 + g) * 64 + lane;
;   float bre[16], bim[16];
; #pragma unroll
;   for (int j = 0; j < 16; ++j) { bre[j] = p.bbre[pi * 16 + j]; bim[j] = p.bbim[pi * 16 + j]; }
;   const float lr = p.lam[pi * 2], li = p.lam[pi * 2 + 1];
.LBB0_422:
	s_ashr_i32 s14, s12, 8
	v_mov_b32_e32 v25, v169
	v_mov_b32_e32 v0, v169
	s_lshl_b32 s1, s12, 4
	s_waitcnt lgkmcnt(0)
	s_barrier
	s_lshl_b32 s0, s14, 12
	s_and_b32 s15, s1, 0xfc0
	v_ashrrev_i32_e32 v10, 2, v0
	v_lshlrev_b32_e32 v0, 4, v0
	s_or_b32 s0, s15, s0
	v_and_b32_e32 v11, 48, v0
	v_add_u32_e32 v0, s0, v10
	s_load_dwordx2 s[0:1], s[18:19], 0x140
	s_and_b32 s16, s12, 3
	s_lshl_b32 s52, s16, 7
	v_ashrrev_i32_e32 v12, 6, v25
	v_lshl_add_u32 v41, s16, 2, v12
	s_waitcnt lgkmcnt(0)
	v_mov_b64_e32 v[2:3], s[0:1]
	v_mad_i64_i32 v[2:3], s[0:1], v0, s60, v[2:3]
	v_lshl_add_u64 v[2:3], v[2:3], 0, s[52:53]
	v_lshlrev_b32_e32 v0, 1, v11
	v_lshl_add_u64 v[6:7], v[2:3], 0, v[0:1]
	global_load_dwordx4 v[2:5], v[6:7], off offset:2880
	s_nop 0
	global_load_dwordx4 v[6:9], v[6:7], off offset:2896
	v_lshlrev_b32_e32 v12, 8, v10
	v_lshlrev_b32_e32 v11, 2, v11
	v_add_u32_e32 v10, s13, v41
	s_load_dwordx2 s[0:1], s[18:19], 0x118
	v_add3_u32 v24, s33, v12, v11
	v_ashrrev_i32_e32 v11, 31, v10
	v_and_b32_e32 v0, 63, v25
	v_lshlrev_b64 v[22:23], 6, v[10:11]
	v_or_b32_e32 v22, v22, v0
	v_lshlrev_b64 v[10:11], 6, v[22:23]
	v_lshl_add_u64 v[18:19], s[10:11], 0, v[10:11]
	s_waitcnt lgkmcnt(0)
	v_lshl_add_u64 v[20:21], s[0:1], 0, v[10:11]
	v_lshl_add_u64 v[22:23], v[22:23], 3, s[8:9]
	v_and_b32_e32 v25, 0xffffffc0, v25
	s_mov_b32 s16, 0
	v_add_u32_e32 v42, s33, v25
	v_mov_b32_e32 v40, 0
	global_load_dwordx4 v[80:83], v[18:19], off offset:16
	global_load_dwordx4 v[84:87], v[20:21], off offset:16
	global_load_dwordx4 v[88:91], v[18:19], off offset:32
	global_load_dwordx4 v[92:95], v[20:21], off offset:32
	global_load_dwordx4 v[96:99], v[18:19], off offset:48
	global_load_dwordx4 v[100:103], v[20:21], off offset:48
	global_load_dwordx4 v[104:107], v[18:19], off
	global_load_dwordx4 v[108:111], v[20:21], off
	global_load_dwordx2 v[112:113], v[22:23], off
	s_waitcnt vmcnt(10)
	v_lshlrev_b32_e32 v10, 16, v2
	v_and_b32_e32 v11, 0xffff0000, v2
	v_lshlrev_b32_e32 v12, 16, v3
	v_and_b32_e32 v13, 0xffff0000, v3
	v_lshlrev_b32_e32 v2, 16, v4
	v_and_b32_e32 v3, 0xffff0000, v4
	v_lshlrev_b32_e32 v4, 16, v5
	v_and_b32_e32 v5, 0xffff0000, v5
	s_waitcnt vmcnt(9)
	v_lshlrev_b32_e32 v14, 16, v6
	v_and_b32_e32 v15, 0xffff0000, v6
	v_lshlrev_b32_e32 v16, 16, v7
	v_and_b32_e32 v17, 0xffff0000, v7
	v_lshlrev_b32_e32 v6, 16, v8
	v_and_b32_e32 v7, 0xffff0000, v8
	v_lshlrev_b32_e32 v8, 16, v9
	v_and_b32_e32 v9, 0xffff0000, v9
	ds_write_b128 v24, v[10:13]
	ds_write_b128 v24, v[2:5] offset:16
	ds_write_b128 v24, v[14:17] offset:32
	ds_write_b128 v24, v[6:9] offset:48
	s_waitcnt lgkmcnt(0)
	s_barrier
	s_waitcnt vmcnt(0)
	v_mov_b32_e32 v2, v80
	v_mov_b32_e32 v3, v81
	v_mov_b32_e32 v4, v82
	v_mov_b32_e32 v5, v83
	v_mov_b32_e32 v6, v84
	v_mov_b32_e32 v7, v85
	v_mov_b32_e32 v8, v86
	v_mov_b32_e32 v9, v87
	v_mov_b32_e32 v30, v88
	v_mov_b32_e32 v31, v89
	v_mov_b32_e32 v32, v90
	v_mov_b32_e32 v33, v91
	v_mov_b32_e32 v10, v92
	v_mov_b32_e32 v11, v93
	v_mov_b32_e32 v12, v94
	v_mov_b32_e32 v13, v95
	v_mov_b32_e32 v34, v96
	v_mov_b32_e32 v35, v97
	v_mov_b32_e32 v36, v98
	v_mov_b32_e32 v37, v99
	v_mov_b32_e32 v14, v100
	v_mov_b32_e32 v15, v101
	v_mov_b32_e32 v16, v102
	v_mov_b32_e32 v17, v103
	v_mov_b32_e32 v44, v104
	v_mov_b32_e32 v45, v105
	v_mov_b32_e32 v46, v106
	v_mov_b32_e32 v47, v107
	s_nop 0
	v_mov_b32_e32 v18, v108
	v_mov_b32_e32 v19, v109
	v_mov_b32_e32 v20, v110
	v_mov_b32_e32 v21, v111
	v_mov_b32_e32 v24, 0
	v_mov_b32_e32 v22, v112
	v_mov_b32_e32 v23, v113
	s_waitcnt vmcnt(8)
	v_mov_b32_e32 v26, v5
	s_waitcnt vmcnt(7)
	v_mov_b32_e32 v27, v9
	s_waitcnt vmcnt(6)
	v_mov_b32_e32 v28, v30
	s_waitcnt vmcnt(5)
	v_mov_b32_e32 v29, v10
	v_mov_b32_e32 v10, v31
	v_mov_b32_e32 v30, v32
	v_mov_b32_e32 v31, v12
	v_mov_b32_e32 v12, v33
	s_waitcnt vmcnt(4)
	v_mov_b32_e32 v32, v34
	s_waitcnt vmcnt(3)
	v_mov_b32_e32 v33, v14
	v_mov_b32_e32 v14, v35
	v_mov_b32_e32 v34, v36
	v_mov_b32_e32 v35, v16
	v_mov_b32_e32 v16, v37
	v_mov_b32_e32 v5, v8
	s_waitcnt vmcnt(2)
	v_mov_b32_e32 v8, v44
	s_waitcnt vmcnt(1)
	v_mov_b32_e32 v9, v18
	v_mov_b32_e32 v18, v45
	v_mov_b32_e32 v36, v46
	v_mov_b32_e32 v37, v20
	v_mov_b32_e32 v20, v47
	v_mov_b32_e32 v38, v2
	v_mov_b32_e32 v39, v6
	v_mov_b32_e32 v6, v3
	s_waitcnt vmcnt(0)
	v_pk_mov_b32 v[2:3], v[22:23], v[22:23] op_sel:[1,0]
	v_mov_b32_e32 v25, 0
	v_permlane32_swap_b32 v8, v18
	v_permlane32_swap_b32 v9, v19
	v_permlane32_swap_b32 v36, v20
	v_permlane32_swap_b32 v37, v21
	v_permlane32_swap_b32 v38, v6
	v_permlane32_swap_b32 v39, v7
	v_permlane32_swap_b32 v4, v26
	v_permlane32_swap_b32 v5, v27
	v_permlane32_swap_b32 v28, v10
	v_permlane32_swap_b32 v29, v11
	v_permlane32_swap_b32 v30, v12
	v_permlane32_swap_b32 v31, v13
	v_permlane32_swap_b32 v32, v14
	v_permlane32_swap_b32 v33, v15
	v_permlane32_swap_b32 v34, v16
	v_permlane32_swap_b32 v35, v17
	v_bfe_u32 v128, v172, 2, 1
	v_bfe_u32 v129, v172, 3, 2
	v_and_b32_e32 v130, 3, v172
	v_lshlrev_b32_e32 v128, 4, v128
	v_lshl_add_u32 v128, v129, 2, v128
	v_add_u32_e32 v128, v128, v130
	v_lshlrev_b32_e32 v128, 8, v128
	v_lshrrev_b32_e32 v129, 5, v172
	v_lshl_add_u32 v126, v129, 2, v128
	v_add_u32_e32 v127, v42, v126
	ds_read2_b32 v[118:119], v127 offset0:0 offset1:2
	ds_read2_b32 v[120:121], v127 offset0:4 offset1:6
	ds_read2_b32 v[122:123], v127 offset0:8 offset1:10
	ds_read2_b32 v[124:125], v127 offset0:12 offset1:14
	s_waitcnt lgkmcnt(0)
; DI void ssm1_item(PREF p, int l, int item, unsigned char* ldsb) {
;     ...
;   for (int t = 0; t < 64; ++t) SSM_STEP(t)
	v_mfma_f32_32x32x2_f32 v[184:199], v118, v8, 0
	v_mfma_f32_32x32x2_f32 v[200:215], v118, v9, 0
	v_mfma_f32_32x32x2_f32 v[216:231], v118, v18, 0
	v_mfma_f32_32x32x2_f32 v[232:247], v118, v19, 0
	v_mfma_f32_32x32x2_f32 v[184:199], v119, v36, v[184:199]
	v_mfma_f32_32x32x2_f32 v[200:215], v119, v37, v[200:215]
	v_mfma_f32_32x32x2_f32 v[216:231], v119, v20, v[216:231]
	v_mfma_f32_32x32x2_f32 v[232:247], v119, v21, v[232:247]
	v_mfma_f32_32x32x2_f32 v[184:199], v120, v38, v[184:199]
	v_mfma_f32_32x32x2_f32 v[200:215], v120, v39, v[200:215]
	v_mfma_f32_32x32x2_f32 v[216:231], v120, v6, v[216:231]
	v_mfma_f32_32x32x2_f32 v[232:247], v120, v7, v[232:247]
	v_mfma_f32_32x32x2_f32 v[184:199], v121, v4, v[184:199]
	v_mfma_f32_32x32x2_f32 v[200:215], v121, v5, v[200:215]
	v_mfma_f32_32x32x2_f32 v[216:231], v121, v26, v[216:231]
	v_mfma_f32_32x32x2_f32 v[232:247], v121, v27, v[232:247]
	v_mfma_f32_32x32x2_f32 v[184:199], v122, v28, v[184:199]
	v_mfma_f32_32x32x2_f32 v[200:215], v122, v29, v[200:215]
	v_mfma_f32_32x32x2_f32 v[216:231], v122, v10, v[216:231]
	v_mfma_f32_32x32x2_f32 v[232:247], v122, v11, v[232:247]
	v_mfma_f32_32x32x2_f32 v[184:199], v123, v30, v[184:199]
	v_mfma_f32_32x32x2_f32 v[200:215], v123, v31, v[200:215]
	v_mfma_f32_32x32x2_f32 v[216:231], v123, v12, v[216:231]
	v_mfma_f32_32x32x2_f32 v[232:247], v123, v13, v[232:247]
	v_mfma_f32_32x32x2_f32 v[184:199], v124, v32, v[184:199]
	v_mfma_f32_32x32x2_f32 v[200:215], v124, v33, v[200:215]
	v_mfma_f32_32x32x2_f32 v[216:231], v124, v14, v[216:231]
	v_mfma_f32_32x32x2_f32 v[232:247], v124, v15, v[232:247]
	v_mfma_f32_32x32x2_f32 v[184:199], v125, v34, v[184:199]
	v_mfma_f32_32x32x2_f32 v[200:215], v125, v35, v[200:215]
	v_mfma_f32_32x32x2_f32 v[216:231], v125, v16, v[216:231]
	v_mfma_f32_32x32x2_f32 v[232:247], v125, v17, v[232:247]
	s_nop 18
	v_permlane32_swap_b32 v184, v216
	s_nop 18
	v_permlane32_swap_b32 v200, v232
	s_nop 16
	v_permlane32_swap_b32 v185, v217
	s_nop 16
	v_permlane32_swap_b32 v201, v233
	s_nop 14
	v_permlane32_swap_b32 v186, v218
	s_nop 14
	v_permlane32_swap_b32 v202, v234
	s_nop 12
	v_permlane32_swap_b32 v187, v219
	s_nop 12
	v_permlane32_swap_b32 v203, v235
	s_nop 10
	v_permlane32_swap_b32 v188, v220
	s_nop 10
	v_permlane32_swap_b32 v204, v236
	s_nop 8
	v_permlane32_swap_b32 v189, v221
	s_nop 8
	v_permlane32_swap_b32 v205, v237
	s_nop 6
	v_permlane32_swap_b32 v190, v222
	s_nop 6
	v_permlane32_swap_b32 v206, v238
	s_nop 4
	v_permlane32_swap_b32 v191, v223
	s_nop 4
	v_permlane32_swap_b32 v207, v239
	s_nop 2
	v_permlane32_swap_b32 v192, v224
	s_nop 2
	v_permlane32_swap_b32 v208, v240
	s_nop 0
	v_permlane32_swap_b32 v193, v225
	s_nop 0
	v_permlane32_swap_b32 v209, v241
	v_permlane32_swap_b32 v194, v226
	v_permlane32_swap_b32 v210, v242
	v_permlane32_swap_b32 v195, v227
	v_permlane32_swap_b32 v211, v243
	v_permlane32_swap_b32 v196, v228
	v_permlane32_swap_b32 v212, v244
	v_permlane32_swap_b32 v197, v229
	v_permlane32_swap_b32 v213, v245
	v_permlane32_swap_b32 v198, v230
	v_permlane32_swap_b32 v214, v246
	v_permlane32_swap_b32 v199, v231
	v_permlane32_swap_b32 v215, v247
	v_mul_f32_e32 v128, v23, v25
	v_mul_f32_e32 v129, v22, v25
	v_fma_f32 v130, v22, v24, -v128
	v_fma_f32 v131, v23, v24, v129
	v_add_f32_e32 v24, v130, v184
	v_add_f32_e32 v25, v131, v200
	v_mul_f32_e32 v128, v23, v25
	v_mul_f32_e32 v129, v22, v25
	v_fma_f32 v130, v22, v24, -v128
	v_fma_f32 v131, v23, v24, v129
	v_add_f32_e32 v24, v130, v185
	v_add_f32_e32 v25, v131, v201
	v_mul_f32_e32 v128, v23, v25
	v_mul_f32_e32 v129, v22, v25
	v_fma_f32 v130, v22, v24, -v128
	v_fma_f32 v131, v23, v24, v129
	v_add_f32_e32 v24, v130, v186
	v_add_f32_e32 v25, v131, v202
	v_mul_f32_e32 v128, v23, v25
	v_mul_f32_e32 v129, v22, v25
	v_fma_f32 v130, v22, v24, -v128
	v_fma_f32 v131, v23, v24, v129
	v_add_f32_e32 v24, v130, v187
	v_add_f32_e32 v25, v131, v203
	v_mul_f32_e32 v128, v23, v25
	v_mul_f32_e32 v129, v22, v25
	v_fma_f32 v130, v22, v24, -v128
	v_fma_f32 v131, v23, v24, v129
	v_add_f32_e32 v24, v130, v188
	v_add_f32_e32 v25, v131, v204
	v_mul_f32_e32 v128, v23, v25
	v_mul_f32_e32 v129, v22, v25
	v_fma_f32 v130, v22, v24, -v128
	v_fma_f32 v131, v23, v24, v129
	v_add_f32_e32 v24, v130, v189
	v_add_f32_e32 v25, v131, v205
	v_mul_f32_e32 v128, v23, v25
	v_mul_f32_e32 v129, v22, v25
	v_fma_f32 v130, v22, v24, -v128
	v_fma_f32 v131, v23, v24, v129
	v_add_f32_e32 v24, v130, v190
	v_add_f32_e32 v25, v131, v206
	v_mul_f32_e32 v128, v23, v25
	v_mul_f32_e32 v129, v22, v25
	v_fma_f32 v130, v22, v24, -v128
	v_fma_f32 v131, v23, v24, v129
	v_add_f32_e32 v24, v130, v191
	v_add_f32_e32 v25, v131, v207
	v_mul_f32_e32 v128, v23, v25
	v_mul_f32_e32 v129, v22, v25
	v_fma_f32 v130, v22, v24, -v128
	v_fma_f32 v131, v23, v24, v129
	v_add_f32_e32 v24, v130, v192
	v_add_f32_e32 v25, v131, v208
	v_mul_f32_e32 v128, v23, v25
	v_mul_f32_e32 v129, v22, v25
	v_fma_f32 v130, v22, v24, -v128
	v_fma_f32 v131, v23, v24, v129
	v_add_f32_e32 v24, v130, v193
	v_add_f32_e32 v25, v131, v209
	v_mul_f32_e32 v128, v23, v25
	v_mul_f32_e32 v129, v22, v25
	v_fma_f32 v130, v22, v24, -v128
	v_fma_f32 v131, v23, v24, v129
	v_add_f32_e32 v24, v130, v194
	v_add_f32_e32 v25, v131, v210
	v_mul_f32_e32 v128, v23, v25
	v_mul_f32_e32 v129, v22, v25
	v_fma_f32 v130, v22, v24, -v128
	v_fma_f32 v131, v23, v24, v129
	v_add_f32_e32 v24, v130, v195
	v_add_f32_e32 v25, v131, v211
	v_mul_f32_e32 v128, v23, v25
	v_mul_f32_e32 v129, v22, v25
	v_fma_f32 v130, v22, v24, -v128
	v_fma_f32 v131, v23, v24, v129
	v_add_f32_e32 v24, v130, v196
	v_add_f32_e32 v25, v131, v212
	v_mul_f32_e32 v128, v23, v25
	v_mul_f32_e32 v129, v22, v25
	v_fma_f32 v130, v22, v24, -v128
	v_fma_f32 v131, v23, v24, v129
; DI void ssm1_item(PREF p, int l, int item, unsigned char* ldsb) {
;     ...
;   for (int t = 0; t < 64; ++t) SSM_STEP(t)
	v_add_f32_e32 v24, v130, v197
	v_add_f32_e32 v25, v131, v213
	v_mul_f32_e32 v128, v23, v25
	v_mul_f32_e32 v129, v22, v25
	v_fma_f32 v130, v22, v24, -v128
	v_fma_f32 v131, v23, v24, v129
	v_add_f32_e32 v24, v130, v198
	v_add_f32_e32 v25, v131, v214
	v_mul_f32_e32 v128, v23, v25
	v_mul_f32_e32 v129, v22, v25
	v_fma_f32 v130, v22, v24, -v128
	v_fma_f32 v131, v23, v24, v129
	v_add_f32_e32 v24, v130, v199
	v_add_f32_e32 v25, v131, v215
	v_mul_f32_e32 v128, v23, v25
	v_mul_f32_e32 v129, v22, v25
	v_fma_f32 v130, v22, v24, -v128
	v_fma_f32 v131, v23, v24, v129
	v_add_f32_e32 v24, v130, v216
	v_add_f32_e32 v25, v131, v232
	v_mul_f32_e32 v128, v23, v25
	v_mul_f32_e32 v129, v22, v25
	v_fma_f32 v130, v22, v24, -v128
	v_fma_f32 v131, v23, v24, v129
	v_add_f32_e32 v24, v130, v217
	v_add_f32_e32 v25, v131, v233
	v_mul_f32_e32 v128, v23, v25
	v_mul_f32_e32 v129, v22, v25
	v_fma_f32 v130, v22, v24, -v128
	v_fma_f32 v131, v23, v24, v129
	v_add_f32_e32 v24, v130, v218
	v_add_f32_e32 v25, v131, v234
	v_mul_f32_e32 v128, v23, v25
	v_mul_f32_e32 v129, v22, v25
	v_fma_f32 v130, v22, v24, -v128
	v_fma_f32 v131, v23, v24, v129
	v_add_f32_e32 v24, v130, v219
	v_add_f32_e32 v25, v131, v235
	v_mul_f32_e32 v128, v23, v25
	v_mul_f32_e32 v129, v22, v25
	v_fma_f32 v130, v22, v24, -v128
	v_fma_f32 v131, v23, v24, v129
	v_add_f32_e32 v24, v130, v220
	v_add_f32_e32 v25, v131, v236
	v_mul_f32_e32 v128, v23, v25
	v_mul_f32_e32 v129, v22, v25
	v_fma_f32 v130, v22, v24, -v128
	v_fma_f32 v131, v23, v24, v129
	v_add_f32_e32 v24, v130, v221
	v_add_f32_e32 v25, v131, v237
	v_mul_f32_e32 v128, v23, v25
	v_mul_f32_e32 v129, v22, v25
	v_fma_f32 v130, v22, v24, -v128
	v_fma_f32 v131, v23, v24, v129
	v_add_f32_e32 v24, v130, v222
	v_add_f32_e32 v25, v131, v238
	v_mul_f32_e32 v128, v23, v25
	v_mul_f32_e32 v129, v22, v25
	v_fma_f32 v130, v22, v24, -v128
	v_fma_f32 v131, v23, v24, v129
	v_add_f32_e32 v24, v130, v223
	v_add_f32_e32 v25, v131, v239
	v_mul_f32_e32 v128, v23, v25
	v_mul_f32_e32 v129, v22, v25
	v_fma_f32 v130, v22, v24, -v128
	v_fma_f32 v131, v23, v24, v129
	v_add_f32_e32 v24, v130, v224
	v_add_f32_e32 v25, v131, v240
	v_mul_f32_e32 v128, v23, v25
	v_mul_f32_e32 v129, v22, v25
	v_fma_f32 v130, v22, v24, -v128
	v_fma_f32 v131, v23, v24, v129
	v_add_f32_e32 v24, v130, v225
	v_add_f32_e32 v25, v131, v241
	v_mul_f32_e32 v128, v23, v25
	v_mul_f32_e32 v129, v22, v25
	v_fma_f32 v130, v22, v24, -v128
	v_fma_f32 v131, v23, v24, v129
	v_add_f32_e32 v24, v130, v226
	v_add_f32_e32 v25, v131, v242
	v_mul_f32_e32 v128, v23, v25
	v_mul_f32_e32 v129, v22, v25
	v_fma_f32 v130, v22, v24, -v128
	v_fma_f32 v131, v23, v24, v129
	v_add_f32_e32 v24, v130, v227
	v_add_f32_e32 v25, v131, v243
	v_mul_f32_e32 v128, v23, v25
	v_mul_f32_e32 v129, v22, v25
	v_fma_f32 v130, v22, v24, -v128
	v_fma_f32 v131, v23, v24, v129
	v_add_f32_e32 v24, v130, v228
	v_add_f32_e32 v25, v131, v244
	v_mul_f32_e32 v128, v23, v25
	v_mul_f32_e32 v129, v22, v25
	v_fma_f32 v130, v22, v24, -v128
	v_fma_f32 v131, v23, v24, v129
	v_add_f32_e32 v24, v130, v229
	v_add_f32_e32 v25, v131, v245
	v_mul_f32_e32 v128, v23, v25
	v_mul_f32_e32 v129, v22, v25
	v_fma_f32 v130, v22, v24, -v128
	v_fma_f32 v131, v23, v24, v129
	v_add_f32_e32 v24, v130, v230
	v_add_f32_e32 v25, v131, v246
	v_mul_f32_e32 v128, v23, v25
	v_mul_f32_e32 v129, v22, v25
	v_fma_f32 v130, v22, v24, -v128
	v_fma_f32 v131, v23, v24, v129
	v_add_f32_e32 v24, v130, v231
	v_add_f32_e32 v25, v131, v247
	v_add_u32_e32 v127, 0x2000, v127
	ds_read2_b32 v[118:119], v127 offset0:0 offset1:2
	ds_read2_b32 v[120:121], v127 offset0:4 offset1:6
	ds_read2_b32 v[122:123], v127 offset0:8 offset1:10
	ds_read2_b32 v[124:125], v127 offset0:12 offset1:14
	s_waitcnt lgkmcnt(0)
	v_mfma_f32_32x32x2_f32 v[184:199], v118, v8, 0
	v_mfma_f32_32x32x2_f32 v[200:215], v118, v9, 0
	v_mfma_f32_32x32x2_f32 v[216:231], v118, v18, 0
	v_mfma_f32_32x32x2_f32 v[232:247], v118, v19, 0
	v_mfma_f32_32x32x2_f32 v[184:199], v119, v36, v[184:199]
	v_mfma_f32_32x32x2_f32 v[200:215], v119, v37, v[200:215]
	v_mfma_f32_32x32x2_f32 v[216:231], v119, v20, v[216:231]
	v_mfma_f32_32x32x2_f32 v[232:247], v119, v21, v[232:247]
	v_mfma_f32_32x32x2_f32 v[184:199], v120, v38, v[184:199]
	v_mfma_f32_32x32x2_f32 v[200:215], v120, v39, v[200:215]
	v_mfma_f32_32x32x2_f32 v[216:231], v120, v6, v[216:231]
	v_mfma_f32_32x32x2_f32 v[232:247], v120, v7, v[232:247]
	v_mfma_f32_32x32x2_f32 v[184:199], v121, v4, v[184:199]
	v_mfma_f32_32x32x2_f32 v[200:215], v121, v5, v[200:215]
	v_mfma_f32_32x32x2_f32 v[216:231], v121, v26, v[216:231]
	v_mfma_f32_32x32x2_f32 v[232:247], v121, v27, v[232:247]
	v_mfma_f32_32x32x2_f32 v[184:199], v122, v28, v[184:199]
	v_mfma_f32_32x32x2_f32 v[200:215], v122, v29, v[200:215]
	v_mfma_f32_32x32x2_f32 v[216:231], v122, v10, v[216:231]
	v_mfma_f32_32x32x2_f32 v[232:247], v122, v11, v[232:247]
	v_mfma_f32_32x32x2_f32 v[184:199], v123, v30, v[184:199]
	v_mfma_f32_32x32x2_f32 v[200:215], v123, v31, v[200:215]
	v_mfma_f32_32x32x2_f32 v[216:231], v123, v12, v[216:231]
	v_mfma_f32_32x32x2_f32 v[232:247], v123, v13, v[232:247]
	v_mfma_f32_32x32x2_f32 v[184:199], v124, v32, v[184:199]
	v_mfma_f32_32x32x2_f32 v[200:215], v124, v33, v[200:215]
	v_mfma_f32_32x32x2_f32 v[216:231], v124, v14, v[216:231]
	v_mfma_f32_32x32x2_f32 v[232:247], v124, v15, v[232:247]
	v_mfma_f32_32x32x2_f32 v[184:199], v125, v34, v[184:199]
	v_mfma_f32_32x32x2_f32 v[200:215], v125, v35, v[200:215]
	v_mfma_f32_32x32x2_f32 v[216:231], v125, v16, v[216:231]
	v_mfma_f32_32x32x2_f32 v[232:247], v125, v17, v[232:247]
	s_nop 18
	v_permlane32_swap_b32 v184, v216
	s_nop 18
	v_permlane32_swap_b32 v200, v232
	s_nop 16
	v_permlane32_swap_b32 v185, v217
; DI void ssm1_item(PREF p, int l, int item, unsigned char* ldsb) {
;     ...
;   for (int t = 0; t < 64; ++t) SSM_STEP(t)
	s_nop 16
	v_permlane32_swap_b32 v201, v233
	s_nop 14
	v_permlane32_swap_b32 v186, v218
	s_nop 14
	v_permlane32_swap_b32 v202, v234
	s_nop 12
	v_permlane32_swap_b32 v187, v219
	s_nop 12
	v_permlane32_swap_b32 v203, v235
	s_nop 10
	v_permlane32_swap_b32 v188, v220
	s_nop 10
	v_permlane32_swap_b32 v204, v236
	s_nop 8
	v_permlane32_swap_b32 v189, v221
	s_nop 8
	v_permlane32_swap_b32 v205, v237
	s_nop 6
	v_permlane32_swap_b32 v190, v222
	s_nop 6
	v_permlane32_swap_b32 v206, v238
	s_nop 4
	v_permlane32_swap_b32 v191, v223
	s_nop 4
	v_permlane32_swap_b32 v207, v239
	s_nop 2
	v_permlane32_swap_b32 v192, v224
	s_nop 2
	v_permlane32_swap_b32 v208, v240
	s_nop 0
	v_permlane32_swap_b32 v193, v225
	s_nop 0
	v_permlane32_swap_b32 v209, v241
	v_permlane32_swap_b32 v194, v226
	v_permlane32_swap_b32 v210, v242
	v_permlane32_swap_b32 v195, v227
	v_permlane32_swap_b32 v211, v243
	v_permlane32_swap_b32 v196, v228
	v_permlane32_swap_b32 v212, v244
	v_permlane32_swap_b32 v197, v229
	v_permlane32_swap_b32 v213, v245
	v_permlane32_swap_b32 v198, v230
	v_permlane32_swap_b32 v214, v246
	v_permlane32_swap_b32 v199, v231
	v_permlane32_swap_b32 v215, v247
	v_mul_f32_e32 v128, v23, v25
	v_mul_f32_e32 v129, v22, v25
	v_fma_f32 v130, v22, v24, -v128
	v_fma_f32 v131, v23, v24, v129
	v_add_f32_e32 v24, v130, v184
	v_add_f32_e32 v25, v131, v200
	v_mul_f32_e32 v128, v23, v25
	v_mul_f32_e32 v129, v22, v25
	v_fma_f32 v130, v22, v24, -v128
	v_fma_f32 v131, v23, v24, v129
	v_add_f32_e32 v24, v130, v185
	v_add_f32_e32 v25, v131, v201
	v_mul_f32_e32 v128, v23, v25
	v_mul_f32_e32 v129, v22, v25
	v_fma_f32 v130, v22, v24, -v128
	v_fma_f32 v131, v23, v24, v129
	v_add_f32_e32 v24, v130, v186
	v_add_f32_e32 v25, v131, v202
	v_mul_f32_e32 v128, v23, v25
	v_mul_f32_e32 v129, v22, v25
	v_fma_f32 v130, v22, v24, -v128
	v_fma_f32 v131, v23, v24, v129
	v_add_f32_e32 v24, v130, v187
	v_add_f32_e32 v25, v131, v203
	v_mul_f32_e32 v128, v23, v25
	v_mul_f32_e32 v129, v22, v25
	v_fma_f32 v130, v22, v24, -v128
	v_fma_f32 v131, v23, v24, v129
	v_add_f32_e32 v24, v130, v188
	v_add_f32_e32 v25, v131, v204
	v_mul_f32_e32 v128, v23, v25
	v_mul_f32_e32 v129, v22, v25
	v_fma_f32 v130, v22, v24, -v128
	v_fma_f32 v131, v23, v24, v129
	v_add_f32_e32 v24, v130, v189
	v_add_f32_e32 v25, v131, v205
	v_mul_f32_e32 v128, v23, v25
	v_mul_f32_e32 v129, v22, v25
	v_fma_f32 v130, v22, v24, -v128
	v_fma_f32 v131, v23, v24, v129
	v_add_f32_e32 v24, v130, v190
	v_add_f32_e32 v25, v131, v206
	v_mul_f32_e32 v128, v23, v25
	v_mul_f32_e32 v129, v22, v25
	v_fma_f32 v130, v22, v24, -v128
	v_fma_f32 v131, v23, v24, v129
	v_add_f32_e32 v24, v130, v191
	v_add_f32_e32 v25, v131, v207
	v_mul_f32_e32 v128, v23, v25
	v_mul_f32_e32 v129, v22, v25
	v_fma_f32 v130, v22, v24, -v128
	v_fma_f32 v131, v23, v24, v129
	v_add_f32_e32 v24, v130, v192
	v_add_f32_e32 v25, v131, v208
	v_mul_f32_e32 v128, v23, v25
	v_mul_f32_e32 v129, v22, v25
	v_fma_f32 v130, v22, v24, -v128
	v_fma_f32 v131, v23, v24, v129
	v_add_f32_e32 v24, v130, v193
	v_add_f32_e32 v25, v131, v209
	v_mul_f32_e32 v128, v23, v25
	v_mul_f32_e32 v129, v22, v25
	v_fma_f32 v130, v22, v24, -v128
	v_fma_f32 v131, v23, v24, v129
	v_add_f32_e32 v24, v130, v194
	v_add_f32_e32 v25, v131, v210
	v_mul_f32_e32 v128, v23, v25
	v_mul_f32_e32 v129, v22, v25
	v_fma_f32 v130, v22, v24, -v128
	v_fma_f32 v131, v23, v24, v129
	v_add_f32_e32 v24, v130, v195
	v_add_f32_e32 v25, v131, v211
	v_mul_f32_e32 v128, v23, v25
	v_mul_f32_e32 v129, v22, v25
	v_fma_f32 v130, v22, v24, -v128
	v_fma_f32 v131, v23, v24, v129
	v_add_f32_e32 v24, v130, v196
	v_add_f32_e32 v25, v131, v212
	v_mul_f32_e32 v128, v23, v25
	v_mul_f32_e32 v129, v22, v25
	v_fma_f32 v130, v22, v24, -v128
	v_fma_f32 v131, v23, v24, v129
	v_add_f32_e32 v24, v130, v197
	v_add_f32_e32 v25, v131, v213
	v_mul_f32_e32 v128, v23, v25
	v_mul_f32_e32 v129, v22, v25
; DI int vbid() { return (int)blockIdx.x * 2 + half_(); }
; DI int vgrid() { return (int)gridDim.x * 2; }
; DI void ssm1_item(PREF p, int l, int item, unsigned char* ldsb) {
;     ...
;   for (int t = 0; t < 64; ++t) SSM_STEP(t)
;   ((float2*)p.hend)[((size_t)(b * 16 + g) * 64 + c) * 64 + lane] = make_float2(hr, hi);
; DI void phase_mix1(PREF p, int l, unsigned char* ldsb) {
;     ...
;   for (int it = vbid(); it < 2048; it += vgrid()) ssm1_item(p, l, it, ldsb);
	v_fma_f32 v130, v22, v24, -v128
	v_fma_f32 v131, v23, v24, v129
	v_add_f32_e32 v24, v130, v198
	v_add_f32_e32 v25, v131, v214
	v_mul_f32_e32 v128, v23, v25
	v_mul_f32_e32 v129, v22, v25
	v_fma_f32 v130, v22, v24, -v128
	v_fma_f32 v131, v23, v24, v129
	v_add_f32_e32 v24, v130, v199
	v_add_f32_e32 v25, v131, v215
	v_mul_f32_e32 v128, v23, v25
	v_mul_f32_e32 v129, v22, v25
	v_fma_f32 v130, v22, v24, -v128
	v_fma_f32 v131, v23, v24, v129
	v_add_f32_e32 v24, v130, v216
	v_add_f32_e32 v25, v131, v232
	v_mul_f32_e32 v128, v23, v25
	v_mul_f32_e32 v129, v22, v25
	v_fma_f32 v130, v22, v24, -v128
	v_fma_f32 v131, v23, v24, v129
	v_add_f32_e32 v24, v130, v217
	v_add_f32_e32 v25, v131, v233
	v_mul_f32_e32 v128, v23, v25
	v_mul_f32_e32 v129, v22, v25
	v_fma_f32 v130, v22, v24, -v128
	v_fma_f32 v131, v23, v24, v129
	v_add_f32_e32 v24, v130, v218
	v_add_f32_e32 v25, v131, v234
	v_mul_f32_e32 v128, v23, v25
	v_mul_f32_e32 v129, v22, v25
	v_fma_f32 v130, v22, v24, -v128
	v_fma_f32 v131, v23, v24, v129
	v_add_f32_e32 v24, v130, v219
	v_add_f32_e32 v25, v131, v235
	v_mul_f32_e32 v128, v23, v25
	v_mul_f32_e32 v129, v22, v25
	v_fma_f32 v130, v22, v24, -v128
	v_fma_f32 v131, v23, v24, v129
	v_add_f32_e32 v24, v130, v220
	v_add_f32_e32 v25, v131, v236
	v_mul_f32_e32 v128, v23, v25
	v_mul_f32_e32 v129, v22, v25
	v_fma_f32 v130, v22, v24, -v128
	v_fma_f32 v131, v23, v24, v129
	v_add_f32_e32 v24, v130, v221
	v_add_f32_e32 v25, v131, v237
	v_mul_f32_e32 v128, v23, v25
	v_mul_f32_e32 v129, v22, v25
	v_fma_f32 v130, v22, v24, -v128
	v_fma_f32 v131, v23, v24, v129
	v_add_f32_e32 v24, v130, v222
	v_add_f32_e32 v25, v131, v238
	v_mul_f32_e32 v128, v23, v25
	v_mul_f32_e32 v129, v22, v25
	v_fma_f32 v130, v22, v24, -v128
	v_fma_f32 v131, v23, v24, v129
	v_add_f32_e32 v24, v130, v223
	v_add_f32_e32 v25, v131, v239
	v_mul_f32_e32 v128, v23, v25
	v_mul_f32_e32 v129, v22, v25
	v_fma_f32 v130, v22, v24, -v128
	v_fma_f32 v131, v23, v24, v129
	v_add_f32_e32 v24, v130, v224
	v_add_f32_e32 v25, v131, v240
	v_mul_f32_e32 v128, v23, v25
	v_mul_f32_e32 v129, v22, v25
	v_fma_f32 v130, v22, v24, -v128
	v_fma_f32 v131, v23, v24, v129
	v_add_f32_e32 v24, v130, v225
	v_add_f32_e32 v25, v131, v241
	v_mul_f32_e32 v128, v23, v25
	v_mul_f32_e32 v129, v22, v25
	v_fma_f32 v130, v22, v24, -v128
	v_fma_f32 v131, v23, v24, v129
	v_add_f32_e32 v24, v130, v226
	v_add_f32_e32 v25, v131, v242
	v_mul_f32_e32 v128, v23, v25
	v_mul_f32_e32 v129, v22, v25
	v_fma_f32 v130, v22, v24, -v128
	v_fma_f32 v131, v23, v24, v129
	v_add_f32_e32 v24, v130, v227
	v_add_f32_e32 v25, v131, v243
	v_mul_f32_e32 v128, v23, v25
	v_mul_f32_e32 v129, v22, v25
	v_fma_f32 v130, v22, v24, -v128
	v_fma_f32 v131, v23, v24, v129
	v_add_f32_e32 v24, v130, v228
	v_add_f32_e32 v25, v131, v244
	v_mul_f32_e32 v128, v23, v25
	v_mul_f32_e32 v129, v22, v25
	v_fma_f32 v130, v22, v24, -v128
	v_fma_f32 v131, v23, v24, v129
	v_add_f32_e32 v24, v130, v229
	v_add_f32_e32 v25, v131, v245
	v_mul_f32_e32 v128, v23, v25
	v_mul_f32_e32 v129, v22, v25
	v_fma_f32 v130, v22, v24, -v128
	v_fma_f32 v131, v23, v24, v129
	v_add_f32_e32 v24, v130, v230
	v_add_f32_e32 v25, v131, v246
	v_mul_f32_e32 v128, v23, v25
	v_mul_f32_e32 v129, v22, v25
	v_fma_f32 v130, v22, v24, -v128
	v_fma_f32 v131, v23, v24, v129
	v_add_f32_e32 v24, v130, v231
	v_add_f32_e32 v25, v131, v247
	v_readlane_b32 s18, v254, 46
	v_readlane_b32 s19, v254, 47
	s_load_dwordx2 s[0:1], s[18:19], 0x188
	v_lshl_add_u32 v2, s14, 4, v41
	v_ashrrev_i32_e32 v3, 31, v2
	v_lshlrev_b64 v[2:3], 15, v[2:3]
	s_lshl_b32 s52, s15, 3
	s_waitcnt lgkmcnt(0)
	v_lshl_add_u64 v[2:3], s[0:1], 0, v[2:3]
	v_lshl_add_u64 v[2:3], v[2:3], 0, s[52:53]
	v_lshlrev_b32_e32 v0, 3, v0
	s_add_i32 s12, s12, s71
	v_lshl_add_u64 v[2:3], v[2:3], 0, v[0:1]
	s_cmpk_gt_i32 s12, 0x7ff
	global_store_dwordx2 v[2:3], v[24:25], off
	s_cbranch_scc0 .LBB0_422
